# stack21 + cache-policy: non-temporal loads for PREP's read-once f32 inputs (x and the weight matrices)
# speedup vs baseline: 1.0054x; 1.0054x over previous
.LBB0_435:
	v_ashrrev_i32_e32 v15, 4, v14
	v_add_u32_e32 v8, s2, v15
	v_ashrrev_i32_e32 v9, 31, v8
	v_and_b32_e32 v0, 60, v7
	v_lshlrev_b64 v[2:3], 14, v[8:9]
	v_lshl_add_u64 v[2:3], s[8:9], 0, v[2:3]
	v_lshlrev_b32_e32 v0, 2, v0
	v_lshl_add_u64 v[2:3], v[2:3], 0, v[0:1]
	global_load_dwordx4 v[2:5], v[2:3], off nt
	v_add_u32_e32 v174, 0x200, v14
	v_add_u32_e32 v167, 0x800, v7
	v_mov_b32_e32 v161, 0
	v_ashrrev_i32_e32 v175, 4, v174
	v_add_u32_e32 v168, s2, v175
	v_ashrrev_i32_e32 v169, 31, v168
	v_and_b32_e32 v160, 60, v167
	v_lshlrev_b64 v[162:163], 14, v[168:169]
	v_lshl_add_u64 v[162:163], s[8:9], 0, v[162:163]
	v_lshlrev_b32_e32 v160, 2, v160
	v_lshl_add_u64 v[162:163], v[162:163], 0, v[160:161]
	global_load_dwordx4 v[162:165], v[162:163], off nt
	s_andn2_b64 vcc, exec, s[84:85]
	s_cbranch_vccz .Lcv_g433
	v_mov_b32_e32 v8, 1.0
	v_mov_b32_e32 v168, 1.0
	s_branch .Lcv_w433

.LBB0_444:
	v_ashrrev_i32_e32 v15, 4, v14
	v_add_u32_e32 v8, s2, v15
	v_ashrrev_i32_e32 v9, 31, v8
	v_and_b32_e32 v0, 60, v7
	v_lshlrev_b64 v[2:3], 14, v[8:9]
	v_lshl_add_u64 v[2:3], s[10:11], 0, v[2:3]
	v_lshlrev_b32_e32 v0, 2, v0
	v_lshl_add_u64 v[2:3], v[2:3], 0, v[0:1]
	global_load_dwordx4 v[2:5], v[2:3], off nt
	v_add_u32_e32 v174, 0x200, v14
	v_add_u32_e32 v167, 0x800, v7
	v_mov_b32_e32 v161, 0
	v_ashrrev_i32_e32 v175, 4, v174
	v_add_u32_e32 v168, s2, v175
	v_ashrrev_i32_e32 v169, 31, v168
	v_and_b32_e32 v160, 60, v167
	v_lshlrev_b64 v[162:163], 14, v[168:169]
	v_lshl_add_u64 v[162:163], s[10:11], 0, v[162:163]
	v_lshlrev_b32_e32 v160, 2, v160
	v_lshl_add_u64 v[162:163], v[162:163], 0, v[160:161]
	global_load_dwordx4 v[162:165], v[162:163], off nt
	s_andn2_b64 vcc, exec, s[84:85]
	s_cbranch_vccz .Lcv_g442
	v_mov_b32_e32 v8, 1.0
	v_mov_b32_e32 v168, 1.0
	s_branch .Lcv_w442

.LBB0_469:
	v_ashrrev_i32_e32 v9, 4, v8
	v_add_u32_e32 v10, s2, v9
	v_ashrrev_i32_e32 v11, 31, v10
	v_lshlrev_b64 v[10:11], 12, v[10:11]
	v_lshlrev_b32_e32 v0, 2, v3
	v_lshl_add_u64 v[10:11], s[10:11], 0, v[10:11]
	v_and_b32_e32 v0, 0xf0, v0
	v_lshl_add_u64 v[10:11], v[10:11], 0, v[0:1]
	global_load_dwordx4 v[10:13], v[10:11], off nt
	v_mul_lo_u32 v9, v9, s27
	v_add3_u32 v0, 0, v9, v0
	v_add_u32_e32 v3, 0x800, v3
	v_add_u32_e32 v168, 0x200, v8
	v_mov_b32_e32 v161, 0
	v_ashrrev_i32_e32 v169, 4, v168
	v_add_u32_e32 v170, s2, v169
	v_ashrrev_i32_e32 v171, 31, v170
	v_lshlrev_b64 v[170:171], 12, v[170:171]
	v_lshlrev_b32_e32 v160, 2, v3
	v_lshl_add_u64 v[170:171], s[10:11], 0, v[170:171]
	v_and_b32_e32 v160, 0xf0, v160
	v_lshl_add_u64 v[170:171], v[170:171], 0, v[160:161]
	global_load_dwordx4 v[170:173], v[170:171], off nt
	v_mul_lo_u32 v169, v169, s27
	v_add3_u32 v160, 0, v169, v160
	v_add_u32_e32 v3, 0x800, v3
	s_waitcnt vmcnt(0)
	ds_write2_b32 v0, v10, v11 offset1:1
	ds_write2_b32 v0, v12, v13 offset0:2 offset1:3
	ds_write2_b32 v160, v170, v171 offset1:1
	ds_write2_b32 v160, v172, v173 offset0:2 offset1:3
	s_branch .LBB0_466

.LBB0_487:
	v_ashrrev_i32_e32 v9, 4, v8
	v_add_u32_e32 v10, s2, v9
	v_ashrrev_i32_e32 v11, 31, v10
	v_lshlrev_b64 v[10:11], 12, v[10:11]
	v_lshlrev_b32_e32 v0, 2, v3
	v_lshl_add_u64 v[10:11], s[8:9], 0, v[10:11]
	v_and_b32_e32 v0, 0xf0, v0
	v_lshl_add_u64 v[10:11], v[10:11], 0, v[0:1]
	global_load_dwordx4 v[10:13], v[10:11], off nt
	v_mul_lo_u32 v9, v9, s27
	v_add3_u32 v0, 0, v9, v0
	v_add_u32_e32 v3, 0x800, v3
	v_add_u32_e32 v168, 0x200, v8
	v_mov_b32_e32 v161, 0
	v_ashrrev_i32_e32 v169, 4, v168
	v_add_u32_e32 v170, s2, v169
	v_ashrrev_i32_e32 v171, 31, v170
	v_lshlrev_b64 v[170:171], 12, v[170:171]
	v_lshlrev_b32_e32 v160, 2, v3
	v_lshl_add_u64 v[170:171], s[8:9], 0, v[170:171]
	v_and_b32_e32 v160, 0xf0, v160
	v_lshl_add_u64 v[170:171], v[170:171], 0, v[160:161]
	global_load_dwordx4 v[170:173], v[170:171], off nt
	v_mul_lo_u32 v169, v169, s27
	v_add3_u32 v160, 0, v169, v160
	v_add_u32_e32 v3, 0x800, v3
	s_waitcnt vmcnt(0)
	ds_write2_b32 v0, v10, v11 offset1:1
	ds_write2_b32 v0, v12, v13 offset0:2 offset1:3
	ds_write2_b32 v160, v170, v171 offset1:1
	ds_write2_b32 v160, v172, v173 offset0:2 offset1:3
	s_branch .LBB0_484

.LBB0_495:
	v_ashrrev_i32_e32 v15, 4, v14
	v_and_b32_e32 v0, 60, v7
	v_add_u32_e32 v8, s2, v15
	v_mov_b64_e32 v[2:3], s[10:11]
	v_mad_i64_i32 v[2:3], s[16:17], v8, s18, v[2:3]
	v_lshlrev_b32_e32 v0, 2, v0
	v_lshl_add_u64 v[2:3], v[2:3], 0, v[0:1]
	global_load_dwordx4 v[2:5], v[2:3], off nt
	v_add_u32_e32 v174, 0x200, v14
	v_add_u32_e32 v167, 0x800, v7
	v_mov_b32_e32 v161, 0
	v_ashrrev_i32_e32 v175, 4, v174
	v_and_b32_e32 v160, 60, v167
	v_add_u32_e32 v168, s2, v175
	v_mov_b64_e32 v[162:163], s[10:11]
	v_mad_i64_i32 v[162:163], s[16:17], v168, s18, v[162:163]
	v_lshlrev_b32_e32 v160, 2, v160
	v_lshl_add_u64 v[162:163], v[162:163], 0, v[160:161]
	global_load_dwordx4 v[162:165], v[162:163], off nt
	s_andn2_b64 vcc, exec, s[88:89]
	s_cbranch_vccz .Lcv_g493
	v_mov_b32_e32 v8, 1.0
	v_mov_b32_e32 v168, 1.0
	s_branch .Lcv_w493

.LBB0_504:
	v_ashrrev_i32_e32 v15, 4, v14
	v_and_b32_e32 v0, 60, v7
	v_add_u32_e32 v8, s2, v15
	v_mov_b64_e32 v[2:3], s[8:9]
	v_mad_i64_i32 v[2:3], s[14:15], v8, s18, v[2:3]
	v_lshlrev_b32_e32 v0, 2, v0
	v_lshl_add_u64 v[2:3], v[2:3], 0, v[0:1]
	global_load_dwordx4 v[2:5], v[2:3], off nt
	v_add_u32_e32 v174, 0x200, v14
	v_add_u32_e32 v167, 0x800, v7
	v_mov_b32_e32 v161, 0
	v_ashrrev_i32_e32 v175, 4, v174
	v_and_b32_e32 v160, 60, v167
	v_add_u32_e32 v168, s2, v175
	v_mov_b64_e32 v[162:163], s[8:9]
	v_mad_i64_i32 v[162:163], s[14:15], v168, s18, v[162:163]
	v_lshlrev_b32_e32 v160, 2, v160
	v_lshl_add_u64 v[162:163], v[162:163], 0, v[160:161]
	global_load_dwordx4 v[162:165], v[162:163], off nt
	s_andn2_b64 vcc, exec, s[88:89]
	s_cbranch_vccz .Lcv_g502
	v_mov_b32_e32 v8, 1.0
	v_mov_b32_e32 v168, 1.0
	s_branch .Lcv_w502

.LBB0_523:
	v_ashrrev_i32_e32 v9, 4, v8
	v_add_u32_e32 v10, s2, v9
	v_ashrrev_i32_e32 v11, 31, v10
	v_lshlrev_b64 v[12:13], 14, v[10:11]
	v_lshlrev_b32_e32 v0, 2, v3
	v_lshl_add_u64 v[12:13], s[10:11], 0, v[12:13]
	v_and_b32_e32 v0, 0xf0, v0
	v_lshl_add_u64 v[12:13], v[12:13], 0, v[0:1]
	v_lshl_add_u64 v[10:11], v[10:11], 2, s[16:17]
	global_load_dword v14, v[10:11], off
	v_mul_lo_u32 v9, v9, s27
	global_load_dwordx4 v[10:13], v[12:13], off nt
	v_add3_u32 v0, 0, v9, v0
	v_add_u32_e32 v3, 0x800, v3
	v_add_u32_e32 v168, 0x200, v8
	v_mov_b32_e32 v161, 0
	v_ashrrev_i32_e32 v169, 4, v168
	v_add_u32_e32 v170, s2, v169
	v_ashrrev_i32_e32 v171, 31, v170
	v_lshlrev_b64 v[172:173], 14, v[170:171]
	v_lshlrev_b32_e32 v160, 2, v3
	v_lshl_add_u64 v[172:173], s[10:11], 0, v[172:173]
	v_and_b32_e32 v160, 0xf0, v160
	v_lshl_add_u64 v[172:173], v[172:173], 0, v[160:161]
	v_lshl_add_u64 v[170:171], v[170:171], 2, s[16:17]
	global_load_dword v174, v[170:171], off
	v_mul_lo_u32 v169, v169, s27
	global_load_dwordx4 v[170:173], v[172:173], off nt
	v_add3_u32 v160, 0, v169, v160
	v_add_u32_e32 v3, 0x800, v3
	s_waitcnt vmcnt(0)
	v_pk_mul_f32 v[10:11], v[10:11], v[14:15] op_sel_hi:[1,0]
	ds_write2_b32 v0, v10, v11 offset1:1
	v_pk_mul_f32 v[10:11], v[12:13], v[14:15] op_sel_hi:[1,0]
	ds_write2_b32 v0, v10, v11 offset0:2 offset1:3
	v_pk_mul_f32 v[170:171], v[170:171], v[174:175] op_sel_hi:[1,0]
	ds_write2_b32 v160, v170, v171 offset1:1
	v_pk_mul_f32 v[170:171], v[172:173], v[174:175] op_sel_hi:[1,0]
	ds_write2_b32 v160, v170, v171 offset0:2 offset1:3
	s_branch .LBB0_520

.LBB0_535:
	v_ashrrev_i32_e32 v9, 4, v8
	v_add_u32_e32 v10, s2, v9
	v_mov_b64_e32 v[12:13], s[10:11]
	s_movk_i32 s0, 0x4800
	v_lshlrev_b32_e32 v0, 2, v3
	v_ashrrev_i32_e32 v11, 31, v10
	v_mad_i64_i32 v[12:13], s[0:1], v10, s0, v[12:13]
	v_and_b32_e32 v0, 0xf0, v0
	v_lshl_add_u64 v[12:13], v[12:13], 0, v[0:1]
	v_lshl_add_u64 v[10:11], v[10:11], 2, s[16:17]
	global_load_dword v14, v[10:11], off
	v_mul_lo_u32 v9, v9, s27
	global_load_dwordx4 v[10:13], v[12:13], off nt
	v_add3_u32 v0, 0, v9, v0
	v_add_u32_e32 v3, 0x800, v3
	v_add_u32_e32 v168, 0x200, v8
	v_mov_b32_e32 v161, 0
	v_ashrrev_i32_e32 v169, 4, v168
	v_add_u32_e32 v170, s2, v169
	v_mov_b64_e32 v[172:173], s[10:11]
	s_movk_i32 s0, 0x4800
	v_lshlrev_b32_e32 v160, 2, v3
	v_ashrrev_i32_e32 v171, 31, v170
	v_mad_i64_i32 v[172:173], s[0:1], v170, s0, v[172:173]
	v_and_b32_e32 v160, 0xf0, v160
	v_lshl_add_u64 v[172:173], v[172:173], 0, v[160:161]
	v_lshl_add_u64 v[170:171], v[170:171], 2, s[16:17]
	global_load_dword v174, v[170:171], off
	v_mul_lo_u32 v169, v169, s27
	global_load_dwordx4 v[170:173], v[172:173], off nt
	v_add3_u32 v160, 0, v169, v160
	v_add_u32_e32 v3, 0x800, v3
	s_waitcnt vmcnt(0)
	v_pk_mul_f32 v[10:11], v[10:11], v[14:15] op_sel_hi:[1,0]
	ds_write2_b32 v0, v10, v11 offset1:1
	v_pk_mul_f32 v[10:11], v[12:13], v[14:15] op_sel_hi:[1,0]
	ds_write2_b32 v0, v10, v11 offset0:2 offset1:3
	v_pk_mul_f32 v[170:171], v[170:171], v[174:175] op_sel_hi:[1,0]
	ds_write2_b32 v160, v170, v171 offset1:1
	v_pk_mul_f32 v[170:171], v[172:173], v[174:175] op_sel_hi:[1,0]
	ds_write2_b32 v160, v170, v171 offset0:2 offset1:3
	s_branch .LBB0_532

.LBB0_548:
	v_cmp_lt_i32_e64 s[0:1], s87, v2
	v_mov_b64_e32 v[10:11], v[2:3]
	s_waitcnt lgkmcnt(0)
	v_mov_b64_e32 v[12:13], v[8:9]
	s_and_saveexec_b64 s[8:9], s[0:1]
	v_add_u32_e32 v10, 0xffff8000, v2
	v_mov_b32_e32 v11, v1
	v_lshlrev_b64 v[10:11], 12, v[10:11]
	v_lshl_add_u64 v[12:13], s[38:39], 0, v[10:11]
	v_mov_b32_e32 v10, v2
	v_mov_b32_e32 v11, v1
	s_or_b64 exec, exec, s[8:9]
	v_lshl_add_u64 v[14:15], v[12:13], 0, v[0:1]
	v_lshlrev_b64 v[12:13], 11, v[10:11]
	v_lshl_add_u64 v[12:13], v[4:5], 0, v[12:13]
	global_load_dwordx4 v[22:25], v[14:15], off nt
	global_load_dwordx4 v[30:33], v[14:15], off offset:1024 nt
	global_load_dwordx4 v[34:37], v[14:15], off offset:2048 nt
	global_load_dwordx4 v[38:41], v[14:15], off offset:3072 nt
	s_waitcnt vmcnt(3)
	v_mul_f32_e32 v26, v23, v23
	v_fmac_f32_e32 v26, v22, v22
	v_and_b32_sdwa v27, v24, v152 dst_sel:DWORD dst_unused:UNUSED_PAD src0_sel:WORD_1 src1_sel:DWORD
	v_and_b32_sdwa v28, v22, v152 dst_sel:DWORD dst_unused:UNUSED_PAD src0_sel:WORD_1 src1_sel:DWORD
	v_fmac_f32_e32 v26, v24, v24
	v_add3_u32 v22, v22, v28, s87
	v_add3_u32 v24, v24, v27, s87
	v_and_b32_sdwa v27, v25, v152 dst_sel:DWORD dst_unused:UNUSED_PAD src0_sel:WORD_1 src1_sel:DWORD
	v_and_b32_sdwa v28, v23, v152 dst_sel:DWORD dst_unused:UNUSED_PAD src0_sel:WORD_1 src1_sel:DWORD
	v_fmac_f32_e32 v26, v25, v25
	v_add3_u32 v25, v25, v27, s87
	v_add3_u32 v23, v23, v28, s87
	v_and_b32_e32 v25, 0xffff0000, v25
	v_and_b32_e32 v27, 0xffff0000, v23
	v_or_b32_sdwa v23, v25, v24 dst_sel:DWORD dst_unused:UNUSED_PAD src0_sel:DWORD src1_sel:WORD_1
	v_or_b32_sdwa v22, v27, v22 dst_sel:DWORD dst_unused:UNUSED_PAD src0_sel:DWORD src1_sel:WORD_1
	global_store_dwordx2 v[12:13], v[22:23], off
	s_waitcnt vmcnt(3)
	v_mul_f32_e32 v27, v31, v31
	v_fmac_f32_e32 v27, v30, v30
	v_fmac_f32_e32 v27, v32, v32
	v_fmac_f32_e32 v27, v33, v33
	v_add_f32_e32 v26, v26, v27
	v_and_b32_sdwa v27, v32, v152 dst_sel:DWORD dst_unused:UNUSED_PAD src0_sel:WORD_1 src1_sel:DWORD
	v_and_b32_sdwa v28, v30, v152 dst_sel:DWORD dst_unused:UNUSED_PAD src0_sel:WORD_1 src1_sel:DWORD
	v_add3_u32 v30, v30, v28, s87
	v_add3_u32 v32, v32, v27, s87
	v_and_b32_sdwa v27, v33, v152 dst_sel:DWORD dst_unused:UNUSED_PAD src0_sel:WORD_1 src1_sel:DWORD
	v_and_b32_sdwa v28, v31, v152 dst_sel:DWORD dst_unused:UNUSED_PAD src0_sel:WORD_1 src1_sel:DWORD
	v_add3_u32 v33, v33, v27, s87
	v_add3_u32 v31, v31, v28, s87
	v_and_b32_e32 v33, 0xffff0000, v33
	v_and_b32_e32 v27, 0xffff0000, v31
	v_or_b32_sdwa v31, v33, v32 dst_sel:DWORD dst_unused:UNUSED_PAD src0_sel:DWORD src1_sel:WORD_1
	v_or_b32_sdwa v30, v27, v30 dst_sel:DWORD dst_unused:UNUSED_PAD src0_sel:DWORD src1_sel:WORD_1
	global_store_dwordx2 v[12:13], v[30:31], off offset:512
	s_waitcnt vmcnt(3)
	v_mul_f32_e32 v27, v35, v35
	v_fmac_f32_e32 v27, v34, v34
	v_fmac_f32_e32 v27, v36, v36
	v_fmac_f32_e32 v27, v37, v37
	v_add_f32_e32 v26, v26, v27
	v_and_b32_sdwa v27, v36, v152 dst_sel:DWORD dst_unused:UNUSED_PAD src0_sel:WORD_1 src1_sel:DWORD
	v_and_b32_sdwa v28, v34, v152 dst_sel:DWORD dst_unused:UNUSED_PAD src0_sel:WORD_1 src1_sel:DWORD
	v_add3_u32 v34, v34, v28, s87
	v_add3_u32 v36, v36, v27, s87
	v_and_b32_sdwa v27, v37, v152 dst_sel:DWORD dst_unused:UNUSED_PAD src0_sel:WORD_1 src1_sel:DWORD
	v_and_b32_sdwa v28, v35, v152 dst_sel:DWORD dst_unused:UNUSED_PAD src0_sel:WORD_1 src1_sel:DWORD
	v_add3_u32 v37, v37, v27, s87
	v_add3_u32 v35, v35, v28, s87
	v_and_b32_e32 v37, 0xffff0000, v37
	v_and_b32_e32 v27, 0xffff0000, v35
	v_or_b32_sdwa v35, v37, v36 dst_sel:DWORD dst_unused:UNUSED_PAD src0_sel:DWORD src1_sel:WORD_1
	v_or_b32_sdwa v34, v27, v34 dst_sel:DWORD dst_unused:UNUSED_PAD src0_sel:DWORD src1_sel:WORD_1
	global_store_dwordx2 v[12:13], v[34:35], off offset:1024
	s_waitcnt vmcnt(3)
	v_mul_f32_e32 v14, v39, v39
	v_fmac_f32_e32 v14, v38, v38
	v_fmac_f32_e32 v14, v40, v40
	v_fmac_f32_e32 v14, v41, v41
	v_add_f32_e32 v26, v26, v14
	v_and_b32_sdwa v14, v40, v152 dst_sel:DWORD dst_unused:UNUSED_PAD src0_sel:WORD_1 src1_sel:DWORD
	v_and_b32_sdwa v15, v38, v152 dst_sel:DWORD dst_unused:UNUSED_PAD src0_sel:WORD_1 src1_sel:DWORD
	v_add3_u32 v38, v38, v15, s87
	v_add3_u32 v14, v40, v14, s87
	v_and_b32_sdwa v15, v41, v152 dst_sel:DWORD dst_unused:UNUSED_PAD src0_sel:WORD_1 src1_sel:DWORD
	v_and_b32_sdwa v40, v39, v152 dst_sel:DWORD dst_unused:UNUSED_PAD src0_sel:WORD_1 src1_sel:DWORD
	v_add3_u32 v15, v41, v15, s87
	v_add3_u32 v39, v39, v40, s87
	v_and_b32_e32 v15, 0xffff0000, v15
	v_and_b32_e32 v39, 0xffff0000, v39
	v_or_b32_sdwa v15, v15, v14 dst_sel:DWORD dst_unused:UNUSED_PAD src0_sel:DWORD src1_sel:WORD_1
	v_or_b32_sdwa v14, v39, v38 dst_sel:DWORD dst_unused:UNUSED_PAD src0_sel:DWORD src1_sel:WORD_1
	global_store_dwordx2 v[12:13], v[14:15], off offset:1536
	ds_bpermute_b32 v12, v16, v26
	s_waitcnt lgkmcnt(0)
	v_add_f32_e32 v12, v26, v12
	ds_bpermute_b32 v13, v17, v12
	s_waitcnt lgkmcnt(0)
	v_add_f32_e32 v12, v12, v13
	ds_bpermute_b32 v13, v18, v12
	s_waitcnt lgkmcnt(0)
	v_add_f32_e32 v12, v12, v13
	ds_bpermute_b32 v13, v19, v12
	s_waitcnt lgkmcnt(0)
	v_add_f32_e32 v12, v12, v13
	ds_bpermute_b32 v13, v20, v12
	s_waitcnt lgkmcnt(0)
	v_add_f32_e32 v12, v12, v13
	ds_bpermute_b32 v13, v21, v12
	s_and_saveexec_b64 s[0:1], vcc
	s_cbranch_execz .LBB0_547
	s_waitcnt lgkmcnt(0)
	v_add_f32_e32 v12, v12, v13
	v_cndmask_b32_e64 v12, 0, v12, s[4:5]
	v_lshl_add_u64 v[10:11], v[10:11], 4, v[6:7]
	global_store_dword v[10:11], v12, off
	s_branch .LBB0_547
